# attn-B tile loop: K/V LDS-DMA loads use SGPR base + 32-bit VGPR offset (four 64-bit VALU adds per tile removed)
# speedup vs baseline: 1.0103x; 1.0022x over previous
.LBB0_704:
	s_add_i32 s12, s10, s27
	s_add_i32 s17, s12, 2
	s_cmp_gt_i32 s17, s11
	s_cbranch_scc1 .Lb_nodma
	s_add_i32 vcc_lo, s18, s28
	s_ashr_i32 vcc_hi, vcc_lo, 31
	s_lshl_b64 vcc, vcc, 8
	s_add_u32 s94, s89, vcc_lo
	s_addc_u32 s95, s50, vcc_hi
	s_add_u32 vcc_lo, s78, vcc_lo
	s_addc_u32 vcc_hi, s88, vcc_hi
	s_add_i32 s17, s23, s29
	s_and_b32 s17, s17, 0xc000
	s_add_i32 s29, s17, s91
	s_add_i32 s17, s17, s51
	s_mov_b32 m0, s29
	s_nop 0
	global_load_lds_dwordx4 v140, s[94:95]
	s_mov_b32 m0, s17
	s_nop 0
	global_load_lds_dwordx4 v142, vcc
	s_add_i32 m0, s29, 0x400
	s_nop 0
	global_load_lds_dwordx4 v144, s[94:95]
	s_add_i32 m0, s17, 0x400
	s_nop 0
	global_load_lds_dwordx4 v146, vcc
	s_waitcnt vmcnt(4) lgkmcnt(0)
	s_barrier
